# GEMM: tile-start store-drain wait removed; redundant sign-extension 64-bit mads dropped from epilogue row addresses (rows are non-negative)
# speedup vs baseline: 1.0063x; 1.0063x over previous
; DI float shx_(float v, int m) { return __int_as_float(__builtin_amdgcn_ds_bpermute((lane_pinned_() ^ m) << 2, __float_as_int(v))); }
; DI int shx_(int v, int m) { return __builtin_amdgcn_ds_bpermute((lane_pinned_() ^ m) << 2, v); }
; DI void gemm_tile(const GD& g, int pm, int pn, bf16_t* shm) {
;     ...
;   const int wid = tid_ >> 6, lane = tid_ & 63, wr = wid >> 2, wc = wid & 3, fr = lane & 15, fq = lane >> 4;
;   float* rsc = (float*)shm + 8 * (64 * 68);
;   if (g.rowscale) {
;     const int row = tid_ >> 1, hf = tid_ & 1;
;     const float4* pp = reinterpret_cast<const float4*>(g.ss + (long)(brow + row) * 32 + hf * 16);
;     const float4 a0 = pp[0], a1 = pp[1], a2 = pp[2], a3 = pp[3];
;     float ssum = (((a0.x + a0.y) + (a0.z + a0.w)) + ((a1.x + a1.y) + (a1.z + a1.w))) + (((a2.x + a2.y) + (a2.z + a2.w)) + ((a3.x + a3.y) + (a3.z + a3.w)));
;     ssum += shx_(ssum, 1);
;     if (hf == 0) rsc[row] = rsqrtf(ssum * (1.f / 2048.f) + EPS);
;   }
.LBB0_450:
	v_mov_b32_e32 v130, v204
	s_lshl_b32 s18, s27, 8
	s_cmp_lg_u32 s2, 0
	v_ashrrev_i32_e32 v2, 6, v130
	s_mov_b32 s3, s77
	s_cselect_b64 s[30:31], -1, 0
	s_cmp_eq_u32 s2, 0
	v_readfirstlane_b32 s4, v2
	s_cbranch_scc1 .LBB0_454
	v_ashrrev_i32_e32 v3, 1, v130
	v_add_u32_e32 v4, s18, v3
	v_ashrrev_i32_e32 v5, 31, v4
	v_and_b32_e32 v20, 1, v130
	v_lshlrev_b64 v[4:5], 7, v[4:5]
	v_lshl_add_u64 v[4:5], s[42:43], 0, v[4:5]
	v_lshlrev_b32_e32 v0, 6, v20
	v_lshl_add_u64 v[16:17], v[4:5], 0, v[0:1]
	global_load_dwordx4 v[4:7], v[16:17], off
	global_load_dwordx4 v[8:11], v[16:17], off offset:16
	global_load_dwordx4 v[12:15], v[16:17], off offset:32
	s_nop 0
	global_load_dwordx4 v[16:19], v[16:17], off offset:48
	v_mov_b32_e32 v0, v208
	v_cmp_eq_u32_e32 vcc, 0, v20
	v_lshlrev_b32_e32 v21, 2, v0
	s_waitcnt vmcnt(3)
	v_add_f32_e32 v0, v4, v5
	v_add_f32_e32 v4, v6, v7
	s_waitcnt vmcnt(2)
	v_add_f32_e32 v5, v8, v9
	v_add_f32_e32 v6, v10, v11
	s_waitcnt vmcnt(1)
	v_add_f32_e32 v7, v12, v13
	v_add_f32_e32 v8, v14, v15
	s_waitcnt vmcnt(0)
	v_add_f32_e32 v9, v16, v17
	v_add_f32_e32 v10, v18, v19
	v_add_f32_e32 v0, v0, v4
	v_add_f32_e32 v4, v5, v6
	v_add_f32_e32 v5, v7, v8
	v_add_f32_e32 v6, v9, v10
	v_add_f32_e32 v0, v0, v4
	v_add_f32_e32 v4, v5, v6
	v_add_f32_e32 v0, v0, v4
	v_xor_b32_e32 v4, 4, v21
	ds_bpermute_b32 v4, v4, v0
	s_and_saveexec_b64 s[2:3], vcc
	s_cbranch_execz .LBB0_453
	s_waitcnt lgkmcnt(0)
	v_add_f32_e32 v0, v0, v4
	v_fmamk_f32 v0, v0, 0x3a000000, v205
	v_mul_f32_e32 v4, 0x4b800000, v0
	v_cmp_gt_f32_e32 vcc, s33, v0
	v_lshl_add_u32 v3, v3, 2, 0
	v_add_u32_e32 v3, 0x22000, v3
	v_cndmask_b32_e32 v0, v0, v4, vcc
	v_rsq_f32_e32 v0, v0
	s_nop 0
	v_mul_f32_e32 v4, 0x45800000, v0
	v_cndmask_b32_e32 v0, v0, v4, vcc
	ds_write_b32 v3, v0

; DI unsigned pk2(float a, float b) { f32x2 v; v[0] = a; v[1] = b; return __builtin_bit_cast(unsigned, __builtin_convertvector(v, bf16v2)); }
; DI float shx_(float v, int m) { return __int_as_float(__builtin_amdgcn_ds_bpermute((lane_pinned_() ^ m) << 2, __float_as_int(v))); }
; DI int shx_(int v, int m) { return __builtin_amdgcn_ds_bpermute((lane_pinned_() ^ m) << 2, v); }
; DI void gemm_tile(const GD& g, int pm, int pn, bf16_t* shm) {
;     ...
;         for (int q = 0; q < 4; ++q) {
;           const int row_l = (pb8 * 4 + q) * 4 + (lane >> 4);
;           float4 v = *reinterpret_cast<const float4*>(stgw + row_l * 68 + c4);
;           const int grow = brow + ai * HALF + wr * 64 + row_l;
;           if (g.epi == 0) {
;             if (g.rowscale) {
;               const float rr = rsc[ai * HALF + wr * 64 + row_l];
;               v.x *= rr; v.y *= rr; v.z *= rr; v.w *= rr;
;             }
;             u32x2 o2; o2[0] = pk2(v.x, v.y); o2[1] = pk2(v.z, v.w);
;             *reinterpret_cast<u32x2*>((bf16_t*)g.C + (long)grow * ldc + gcol) = o2;
;           } else if (g.epi == 2) {
;             const float rr = rsc[ai * HALF + wr * 64 + row_l];
;             v.x *= rr; v.y *= rr; v.z *= rr; v.w *= rr;
;             *reinterpret_cast<float4*>((float*)g.C + (long)grow * ldc + gcol) = v;
;           } else {
;             float4 x = xs[q];
;             x.x += v.x; x.y += v.y; x.z += v.z; x.w += v.w;
;             *reinterpret_cast<float4*>((float*)g.C + (long)grow * ldc + gcol) = x;
;             if (g.gnext) {
;               u32x2 o2; o2[0] = pk2(x.x * gn.x, x.y * gn.y); o2[1] = pk2(x.z * gn.z, x.w * gn.w);
;               *reinterpret_cast<u32x2*>(g.hbout + (long)grow * DM + gcol) = o2;
;               float sq = (x.x * x.x + x.y * x.y) + (x.z * x.z + x.w * x.w);
;               sq += shx_(sq, 1); sq += shx_(sq, 2); sq += shx_(sq, 4); sq += shx_(sq, 8);
;               if ((lane & 15) == 0) g.ss[(long)grow * 32 + pn * 4 + wc] = sq;
;             }
.LBB0_625:
	v_mad_u64_u32 v[104:105], s[2:3], v96, s78, 0
	v_lshl_add_u64 v[104:105], v[104:105], 2, s[34:35]
	s_waitcnt vmcnt(0) lgkmcnt(0)
	v_pk_add_f32 v[90:91], v[14:15], v[86:87]
	v_pk_add_f32 v[92:93], v[16:17], v[88:89]
	v_lshl_add_u64 v[104:105], v[94:95], 2, v[104:105]
	s_cmp_eq_u64 s[80:81], 0
	global_store_dwordx4 v[104:105], v[90:93], off
	s_cbranch_scc1 .LBB0_629
	v_pk_mul_f32 v[104:105], v[82:83], v[90:91]
	v_pk_mul_f32 v[106:107], v[84:85], v[92:93]
	v_cvt_pk_bf16_f32 v104, v104, v105
	v_cvt_pk_bf16_f32 v105, v106, v107
	v_lshlrev_b64 v[106:107], 12, v[96:97]
	v_pk_mul_f32 v[90:91], v[90:91], v[90:91]
	v_pk_mul_f32 v[92:93], v[92:93], v[92:93]
	v_lshl_add_u64 v[106:107], s[20:21], 0, v[106:107]
	v_add_f32_e32 v0, v92, v93
	v_add_f32_e32 v90, v90, v91
	v_lshl_add_u64 v[106:107], v[94:95], 1, v[106:107]
	v_add_f32_e32 v0, v90, v0
	global_store_dwordx2 v[106:107], v[104:105], off
	s_nop 1
	v_mov_b32_dpp v90, v0 quad_perm:[1,0,3,2] row_mask:0xf bank_mask:0xf
	s_waitcnt lgkmcnt(0)
	v_add_f32_e32 v0, v0, v90
	s_nop 1
	v_mov_b32_dpp v90, v0 quad_perm:[2,3,0,1] row_mask:0xf bank_mask:0xf
	s_waitcnt lgkmcnt(0)
	v_add_f32_e32 v0, v0, v90
	s_nop 1
	v_mov_b32_dpp v90, v0 row_half_mirror row_mask:0xf bank_mask:0xf
	s_waitcnt lgkmcnt(0)
	v_add_f32_e32 v90, v0, v90
	s_nop 1
	v_mov_b32_dpp v91, v90 row_ror:8 row_mask:0xf bank_mask:0xf
	s_and_saveexec_b64 s[2:3], s[4:5]
	s_cbranch_execz .LBB0_628
	v_lshlrev_b64 v[92:93], 7, v[96:97]
	v_lshl_add_u64 v[92:93], s[42:43], 0, v[92:93]
	v_lshl_add_u64 v[92:93], s[0:1], 2, v[92:93]
	v_lshlrev_b32_e32 v0, 2, v139
	v_lshl_add_u64 v[92:93], v[92:93], 0, v[0:1]
	s_waitcnt lgkmcnt(0)
	v_add_f32_e32 v0, v90, v91
	global_store_dword v[92:93], v0, off

; DI unsigned pk2(float a, float b) { f32x2 v; v[0] = a; v[1] = b; return __builtin_bit_cast(unsigned, __builtin_convertvector(v, bf16v2)); }
; DI void gemm_tile(const GD& g, int pm, int pn, bf16_t* shm) {
;     ...
;           if (g.epi == 0) {
;             if (g.rowscale) {
;               const float rr = rsc[ai * HALF + wr * 64 + row_l];
;               v.x *= rr; v.y *= rr; v.z *= rr; v.w *= rr;
;             }
;             u32x2 o2; o2[0] = pk2(v.x, v.y); o2[1] = pk2(v.z, v.w);
;             *reinterpret_cast<u32x2*>((bf16_t*)g.C + (long)grow * ldc + gcol) = o2;
.LBB0_635:
	s_waitcnt lgkmcnt(0)
	v_cvt_pk_bf16_f32 v86, v86, v87
	v_cvt_pk_bf16_f32 v87, v88, v89
	v_mad_u64_u32 v[88:89], s[2:3], v96, s78, 0
	v_lshl_add_u64 v[88:89], v[88:89], 1, s[34:35]
	v_lshl_add_u64 v[88:89], v[94:95], 1, v[88:89]
	global_store_dwordx2 v[88:89], v[86:87], off

; DI unsigned pk2(float a, float b) { f32x2 v; v[0] = a; v[1] = b; return __builtin_bit_cast(unsigned, __builtin_convertvector(v, bf16v2)); }
; DI float shx_(float v, int m) { return __int_as_float(__builtin_amdgcn_ds_bpermute((lane_pinned_() ^ m) << 2, __float_as_int(v))); }
; DI int shx_(int v, int m) { return __builtin_amdgcn_ds_bpermute((lane_pinned_() ^ m) << 2, v); }
; DI void gemm_tile(const GD& g, int pm, int pn, bf16_t* shm) {
;     ...
;         for (int q = 0; q < 4; ++q) {
;           const int row_l = (pb8 * 4 + q) * 4 + (lane >> 4);
;           float4 v = *reinterpret_cast<const float4*>(stgw + row_l * 68 + c4);
;           const int grow = brow + ai * HALF + wr * 64 + row_l;
;           if (g.epi == 0) {
;             if (g.rowscale) {
;               const float rr = rsc[ai * HALF + wr * 64 + row_l];
;               v.x *= rr; v.y *= rr; v.z *= rr; v.w *= rr;
;             }
;             u32x2 o2; o2[0] = pk2(v.x, v.y); o2[1] = pk2(v.z, v.w);
;             *reinterpret_cast<u32x2*>((bf16_t*)g.C + (long)grow * ldc + gcol) = o2;
;           } else if (g.epi == 2) {
;             const float rr = rsc[ai * HALF + wr * 64 + row_l];
;             v.x *= rr; v.y *= rr; v.z *= rr; v.w *= rr;
;             *reinterpret_cast<float4*>((float*)g.C + (long)grow * ldc + gcol) = v;
;           } else {
;             float4 x = xs[q];
;             x.x += v.x; x.y += v.y; x.z += v.z; x.w += v.w;
;             *reinterpret_cast<float4*>((float*)g.C + (long)grow * ldc + gcol) = x;
;             if (g.gnext) {
;               u32x2 o2; o2[0] = pk2(x.x * gn.x, x.y * gn.y); o2[1] = pk2(x.z * gn.z, x.w * gn.w);
;               *reinterpret_cast<u32x2*>(g.hbout + (long)grow * DM + gcol) = o2;
;               float sq = (x.x * x.x + x.y * x.y) + (x.z * x.z + x.w * x.w);
;               sq += shx_(sq, 1); sq += shx_(sq, 2); sq += shx_(sq, 4); sq += shx_(sq, 8);
;               if ((lane & 15) == 0) g.ss[(long)grow * 32 + pn * 4 + wc] = sq;
;             }
.LBB0_641:
	v_mad_u64_u32 v[104:105], s[2:3], v96, s78, 0
	v_lshl_add_u64 v[104:105], v[104:105], 2, s[34:35]
	s_waitcnt lgkmcnt(0)
	v_pk_add_f32 v[90:91], v[6:7], v[86:87]
	v_pk_add_f32 v[92:93], v[8:9], v[88:89]
	v_lshl_add_u64 v[104:105], v[94:95], 2, v[104:105]
	s_cmp_eq_u64 s[80:81], 0
	global_store_dwordx4 v[104:105], v[90:93], off
	s_cbranch_scc1 .LBB0_645
	v_pk_mul_f32 v[104:105], v[82:83], v[90:91]
	v_pk_mul_f32 v[106:107], v[84:85], v[92:93]
	v_cvt_pk_bf16_f32 v104, v104, v105
	v_cvt_pk_bf16_f32 v105, v106, v107
	v_lshlrev_b64 v[106:107], 12, v[96:97]
	v_pk_mul_f32 v[90:91], v[90:91], v[90:91]
	v_pk_mul_f32 v[92:93], v[92:93], v[92:93]
	v_lshl_add_u64 v[106:107], s[20:21], 0, v[106:107]
	v_add_f32_e32 v0, v92, v93
	v_add_f32_e32 v90, v90, v91
	v_lshl_add_u64 v[106:107], v[94:95], 1, v[106:107]
	v_add_f32_e32 v0, v90, v0
	global_store_dwordx2 v[106:107], v[104:105], off
	s_nop 1
	v_mov_b32_dpp v90, v0 quad_perm:[1,0,3,2] row_mask:0xf bank_mask:0xf
	s_waitcnt lgkmcnt(0)
	v_add_f32_e32 v0, v0, v90
	s_nop 1
	v_mov_b32_dpp v90, v0 quad_perm:[2,3,0,1] row_mask:0xf bank_mask:0xf
	s_waitcnt lgkmcnt(0)
	v_add_f32_e32 v0, v0, v90
	s_nop 1
	v_mov_b32_dpp v90, v0 row_half_mirror row_mask:0xf bank_mask:0xf
	s_waitcnt lgkmcnt(0)
	v_add_f32_e32 v90, v0, v90
	s_nop 1
	v_mov_b32_dpp v91, v90 row_ror:8 row_mask:0xf bank_mask:0xf
	s_and_saveexec_b64 s[2:3], s[4:5]
	s_cbranch_execz .LBB0_644
	v_lshlrev_b64 v[92:93], 7, v[96:97]
	v_lshl_add_u64 v[92:93], s[42:43], 0, v[92:93]
	v_lshl_add_u64 v[92:93], s[0:1], 2, v[92:93]
	v_lshlrev_b32_e32 v0, 2, v139
	v_lshl_add_u64 v[92:93], v[92:93], 0, v[0:1]
	s_waitcnt lgkmcnt(0)
	v_add_f32_e32 v0, v90, v91
	global_store_dword v[92:93], v0, off

; DI unsigned pk2(float a, float b) { f32x2 v; v[0] = a; v[1] = b; return __builtin_bit_cast(unsigned, __builtin_convertvector(v, bf16v2)); }
; DI float shx_(float v, int m) { return __int_as_float(__builtin_amdgcn_ds_bpermute((lane_pinned_() ^ m) << 2, __float_as_int(v))); }
; DI int shx_(int v, int m) { return __builtin_amdgcn_ds_bpermute((lane_pinned_() ^ m) << 2, v); }
; DI void gemm_tile(const GD& g, int pm, int pn, bf16_t* shm) {
;     ...
;         for (int q = 0; q < 4; ++q) {
;           const int row_l = (pb8 * 4 + q) * 4 + (lane >> 4);
;           float4 v = *reinterpret_cast<const float4*>(stgw + row_l * 68 + c4);
;           const int grow = brow + ai * HALF + wr * 64 + row_l;
;           if (g.epi == 0) {
;             if (g.rowscale) {
;               const float rr = rsc[ai * HALF + wr * 64 + row_l];
;               v.x *= rr; v.y *= rr; v.z *= rr; v.w *= rr;
;             }
;             u32x2 o2; o2[0] = pk2(v.x, v.y); o2[1] = pk2(v.z, v.w);
;             *reinterpret_cast<u32x2*>((bf16_t*)g.C + (long)grow * ldc + gcol) = o2;
;           } else if (g.epi == 2) {
;             const float rr = rsc[ai * HALF + wr * 64 + row_l];
;             v.x *= rr; v.y *= rr; v.z *= rr; v.w *= rr;
;             *reinterpret_cast<float4*>((float*)g.C + (long)grow * ldc + gcol) = v;
;           } else {
;             float4 x = xs[q];
;             x.x += v.x; x.y += v.y; x.z += v.z; x.w += v.w;
;             *reinterpret_cast<float4*>((float*)g.C + (long)grow * ldc + gcol) = x;
;             if (g.gnext) {
;               u32x2 o2; o2[0] = pk2(x.x * gn.x, x.y * gn.y); o2[1] = pk2(x.z * gn.z, x.w * gn.w);
;               *reinterpret_cast<u32x2*>(g.hbout + (long)grow * DM + gcol) = o2;
;               float sq = (x.x * x.x + x.y * x.y) + (x.z * x.z + x.w * x.w);
;               sq += shx_(sq, 1); sq += shx_(sq, 2); sq += shx_(sq, 4); sq += shx_(sq, 8);
;               if ((lane & 15) == 0) g.ss[(long)grow * 32 + pn * 4 + wc] = sq;
;             }
.LBB0_657:
	v_mad_u64_u32 v[104:105], s[2:3], v96, s78, 0
	v_lshl_add_u64 v[104:105], v[104:105], 2, s[34:35]
	s_waitcnt lgkmcnt(0)
	v_pk_add_f32 v[90:91], v[10:11], v[86:87]
	v_pk_add_f32 v[92:93], v[12:13], v[88:89]
	v_lshl_add_u64 v[104:105], v[94:95], 2, v[104:105]
	s_cmp_eq_u64 s[80:81], 0
	global_store_dwordx4 v[104:105], v[90:93], off
	s_cbranch_scc1 .LBB0_661
	v_pk_mul_f32 v[104:105], v[82:83], v[90:91]
	v_pk_mul_f32 v[106:107], v[84:85], v[92:93]
	v_cvt_pk_bf16_f32 v104, v104, v105
	v_cvt_pk_bf16_f32 v105, v106, v107
	v_lshlrev_b64 v[106:107], 12, v[96:97]
	v_pk_mul_f32 v[90:91], v[90:91], v[90:91]
	v_pk_mul_f32 v[92:93], v[92:93], v[92:93]
	v_lshl_add_u64 v[106:107], s[20:21], 0, v[106:107]
	v_add_f32_e32 v0, v92, v93
	v_add_f32_e32 v90, v90, v91
	v_lshl_add_u64 v[106:107], v[94:95], 1, v[106:107]
	v_add_f32_e32 v0, v90, v0
	global_store_dwordx2 v[106:107], v[104:105], off
	s_nop 1
	v_mov_b32_dpp v90, v0 quad_perm:[1,0,3,2] row_mask:0xf bank_mask:0xf
	s_waitcnt lgkmcnt(0)
	v_add_f32_e32 v0, v0, v90
	s_nop 1
	v_mov_b32_dpp v90, v0 quad_perm:[2,3,0,1] row_mask:0xf bank_mask:0xf
	s_waitcnt lgkmcnt(0)
	v_add_f32_e32 v0, v0, v90
	s_nop 1
	v_mov_b32_dpp v90, v0 row_half_mirror row_mask:0xf bank_mask:0xf
	s_waitcnt lgkmcnt(0)
	v_add_f32_e32 v90, v0, v90
	s_nop 1
	v_mov_b32_dpp v91, v90 row_ror:8 row_mask:0xf bank_mask:0xf
	s_and_saveexec_b64 s[2:3], s[4:5]
	s_cbranch_execz .LBB0_660
	v_lshlrev_b64 v[92:93], 7, v[96:97]
	v_lshl_add_u64 v[92:93], s[42:43], 0, v[92:93]
	v_lshl_add_u64 v[92:93], s[0:1], 2, v[92:93]
	v_lshlrev_b32_e32 v0, 2, v139
	v_lshl_add_u64 v[92:93], v[92:93], 0, v[0:1]
	s_waitcnt lgkmcnt(0)
	v_add_f32_e32 v0, v90, v91
	global_store_dword v[92:93], v0, off

; DI unsigned pk2(float a, float b) { f32x2 v; v[0] = a; v[1] = b; return __builtin_bit_cast(unsigned, __builtin_convertvector(v, bf16v2)); }
; DI float shx_(float v, int m) { return __int_as_float(__builtin_amdgcn_ds_bpermute((lane_pinned_() ^ m) << 2, __float_as_int(v))); }
; DI int shx_(int v, int m) { return __builtin_amdgcn_ds_bpermute((lane_pinned_() ^ m) << 2, v); }
; DI void gemm_tile(const GD& g, int pm, int pn, bf16_t* shm) {
;     ...
;         for (int q = 0; q < 4; ++q) {
;           const int row_l = (pb8 * 4 + q) * 4 + (lane >> 4);
;           float4 v = *reinterpret_cast<const float4*>(stgw + row_l * 68 + c4);
;           const int grow = brow + ai * HALF + wr * 64 + row_l;
;           if (g.epi == 0) {
;             if (g.rowscale) {
;               const float rr = rsc[ai * HALF + wr * 64 + row_l];
;               v.x *= rr; v.y *= rr; v.z *= rr; v.w *= rr;
;             }
;             u32x2 o2; o2[0] = pk2(v.x, v.y); o2[1] = pk2(v.z, v.w);
;             *reinterpret_cast<u32x2*>((bf16_t*)g.C + (long)grow * ldc + gcol) = o2;
;           } else if (g.epi == 2) {
;             const float rr = rsc[ai * HALF + wr * 64 + row_l];
;             v.x *= rr; v.y *= rr; v.z *= rr; v.w *= rr;
;             *reinterpret_cast<float4*>((float*)g.C + (long)grow * ldc + gcol) = v;
;           } else {
;             float4 x = xs[q];
;             x.x += v.x; x.y += v.y; x.z += v.z; x.w += v.w;
;             *reinterpret_cast<float4*>((float*)g.C + (long)grow * ldc + gcol) = x;
;             if (g.gnext) {
;               u32x2 o2; o2[0] = pk2(x.x * gn.x, x.y * gn.y); o2[1] = pk2(x.z * gn.z, x.w * gn.w);
;               *reinterpret_cast<u32x2*>(g.hbout + (long)grow * DM + gcol) = o2;
;               float sq = (x.x * x.x + x.y * x.y) + (x.z * x.z + x.w * x.w);
;               sq += shx_(sq, 1); sq += shx_(sq, 2); sq += shx_(sq, 4); sq += shx_(sq, 8);
;               if ((lane & 15) == 0) g.ss[(long)grow * 32 + pn * 4 + wc] = sq;
;             }
.LBB0_673:
	v_mad_u64_u32 v[104:105], s[2:3], v96, s78, 0
	v_lshl_add_u64 v[104:105], v[104:105], 2, s[34:35]
	s_waitcnt lgkmcnt(0)
	v_pk_add_f32 v[90:91], v[2:3], v[86:87]
	v_pk_add_f32 v[92:93], v[4:5], v[88:89]
	v_lshl_add_u64 v[104:105], v[94:95], 2, v[104:105]
	s_cmp_eq_u64 s[80:81], 0
	global_store_dwordx4 v[104:105], v[90:93], off
	s_cbranch_scc1 .LBB0_677
	v_pk_mul_f32 v[104:105], v[82:83], v[90:91]
	v_pk_mul_f32 v[106:107], v[84:85], v[92:93]
	v_cvt_pk_bf16_f32 v104, v104, v105
	v_cvt_pk_bf16_f32 v105, v106, v107
	v_lshlrev_b64 v[106:107], 12, v[96:97]
	v_pk_mul_f32 v[90:91], v[90:91], v[90:91]
	v_pk_mul_f32 v[92:93], v[92:93], v[92:93]
	v_lshl_add_u64 v[106:107], s[20:21], 0, v[106:107]
	v_add_f32_e32 v0, v92, v93
	v_add_f32_e32 v90, v90, v91
	v_lshl_add_u64 v[106:107], v[94:95], 1, v[106:107]
	v_add_f32_e32 v0, v90, v0
	global_store_dwordx2 v[106:107], v[104:105], off
	s_nop 1
	v_mov_b32_dpp v90, v0 quad_perm:[1,0,3,2] row_mask:0xf bank_mask:0xf
	s_waitcnt lgkmcnt(0)
	v_add_f32_e32 v0, v0, v90
	s_nop 1
	v_mov_b32_dpp v90, v0 quad_perm:[2,3,0,1] row_mask:0xf bank_mask:0xf
	s_waitcnt lgkmcnt(0)
	v_add_f32_e32 v0, v0, v90
	s_nop 1
	v_mov_b32_dpp v90, v0 row_half_mirror row_mask:0xf bank_mask:0xf
	s_waitcnt lgkmcnt(0)
	v_add_f32_e32 v90, v0, v90
	s_nop 1
	v_mov_b32_dpp v91, v90 row_ror:8 row_mask:0xf bank_mask:0xf
	s_and_saveexec_b64 s[2:3], s[4:5]
	s_cbranch_execz .LBB0_676
	v_lshlrev_b64 v[92:93], 7, v[96:97]
	v_lshl_add_u64 v[92:93], s[42:43], 0, v[92:93]
	v_lshl_add_u64 v[92:93], s[0:1], 2, v[92:93]
	v_lshlrev_b32_e32 v0, 2, v139
	v_lshl_add_u64 v[92:93], v[92:93], 0, v[0:1]
	s_waitcnt lgkmcnt(0)
	v_add_f32_e32 v0, v90, v91
	global_store_dword v[92:93], v0, off

; DI unsigned pk2(float a, float b) { f32x2 v; v[0] = a; v[1] = b; return __builtin_bit_cast(unsigned, __builtin_convertvector(v, bf16v2)); }
; DI void gemm_tile(const GD& g, int pm, int pn, bf16_t* shm) {
;     ...
;           if (g.epi == 0) {
;             if (g.rowscale) {
;               const float rr = rsc[ai * HALF + wr * 64 + row_l];
;               v.x *= rr; v.y *= rr; v.z *= rr; v.w *= rr;
;             }
;             u32x2 o2; o2[0] = pk2(v.x, v.y); o2[1] = pk2(v.z, v.w);
;             *reinterpret_cast<u32x2*>((bf16_t*)g.C + (long)grow * ldc + gcol) = o2;
.LBB0_695:
	s_waitcnt lgkmcnt(0)
	v_cvt_pk_bf16_f32 v86, v86, v87
	v_cvt_pk_bf16_f32 v87, v88, v89
	v_mad_u64_u32 v[88:89], s[2:3], v96, s78, 0
	v_lshl_add_u64 v[88:89], v[88:89], 1, s[34:35]
	v_lshl_add_u64 v[88:89], v[94:95], 1, v[88:89]
	global_store_dwordx2 v[88:89], v[86:87], off
	v_cndmask_b32_e64 v0, 0, 1, s[54:55]
	v_cmp_ne_u32_e64 s[12:13], 1, v0
	s_andn2_b64 vcc, exec, s[54:55]
	s_cbranch_vccz .LBB0_679
	s_branch .LBB0_680

; DI unsigned pk2(float a, float b) { f32x2 v; v[0] = a; v[1] = b; return __builtin_bit_cast(unsigned, __builtin_convertvector(v, bf16v2)); }
; DI void gemm_tile(const GD& g, int pm, int pn, bf16_t* shm) {
;     ...
;           if (g.epi == 0) {
;             if (g.rowscale) {
;               const float rr = rsc[ai * HALF + wr * 64 + row_l];
;               v.x *= rr; v.y *= rr; v.z *= rr; v.w *= rr;
;             }
;             u32x2 o2; o2[0] = pk2(v.x, v.y); o2[1] = pk2(v.z, v.w);
;             *reinterpret_cast<u32x2*>((bf16_t*)g.C + (long)grow * ldc + gcol) = o2;
.LBB0_761:
	s_waitcnt lgkmcnt(0)
	v_cvt_pk_bf16_f32 v86, v86, v87
	v_cvt_pk_bf16_f32 v87, v88, v89
	v_mad_u64_u32 v[88:89], s[2:3], v96, s78, 0
	v_lshl_add_u64 v[88:89], v[88:89], 1, s[34:35]
	v_lshl_add_u64 v[88:89], v[94:95], 1, v[88:89]
	global_store_dwordx2 v[88:89], v[86:87], off
	s_and_b64 vcc, exec, s[12:13]
	s_cbranch_vccz .LBB0_745
	s_branch .LBB0_746

; DI unsigned pk2(float a, float b) { f32x2 v; v[0] = a; v[1] = b; return __builtin_bit_cast(unsigned, __builtin_convertvector(v, bf16v2)); }
; DI float shx_(float v, int m) { return __int_as_float(__builtin_amdgcn_ds_bpermute((lane_pinned_() ^ m) << 2, __float_as_int(v))); }
; DI int shx_(int v, int m) { return __builtin_amdgcn_ds_bpermute((lane_pinned_() ^ m) << 2, v); }
; DI void gemm_tile(const GD& g, int pm, int pn, bf16_t* shm) {
;     ...
;         for (int q = 0; q < 4; ++q) {
;           const int row_l = (pb8 * 4 + q) * 4 + (lane >> 4);
;           float4 v = *reinterpret_cast<const float4*>(stgw + row_l * 68 + c4);
;           const int grow = brow + ai * HALF + wr * 64 + row_l;
;           if (g.epi == 0) {
;             if (g.rowscale) {
;               const float rr = rsc[ai * HALF + wr * 64 + row_l];
;               v.x *= rr; v.y *= rr; v.z *= rr; v.w *= rr;
;             }
;             u32x2 o2; o2[0] = pk2(v.x, v.y); o2[1] = pk2(v.z, v.w);
;             *reinterpret_cast<u32x2*>((bf16_t*)g.C + (long)grow * ldc + gcol) = o2;
;           } else if (g.epi == 2) {
;             const float rr = rsc[ai * HALF + wr * 64 + row_l];
;             v.x *= rr; v.y *= rr; v.z *= rr; v.w *= rr;
;             *reinterpret_cast<float4*>((float*)g.C + (long)grow * ldc + gcol) = v;
;           } else {
;             float4 x = xs[q];
;             x.x += v.x; x.y += v.y; x.z += v.z; x.w += v.w;
;             *reinterpret_cast<float4*>((float*)g.C + (long)grow * ldc + gcol) = x;
;             if (g.gnext) {
;               u32x2 o2; o2[0] = pk2(x.x * gn.x, x.y * gn.y); o2[1] = pk2(x.z * gn.z, x.w * gn.w);
;               *reinterpret_cast<u32x2*>(g.hbout + (long)grow * DM + gcol) = o2;
;               float sq = (x.x * x.x + x.y * x.y) + (x.z * x.z + x.w * x.w);
;               sq += shx_(sq, 1); sq += shx_(sq, 2); sq += shx_(sq, 4); sq += shx_(sq, 8);
;               if ((lane & 15) == 0) g.ss[(long)grow * 32 + pn * 4 + wc] = sq;
;             }
.LBB0_817:
	v_mad_u64_u32 v[102:103], s[2:3], v96, s78, 0
	v_lshl_add_u64 v[102:103], v[102:103], 2, s[34:35]
	s_waitcnt vmcnt(0) lgkmcnt(0)
	v_pk_add_f32 v[90:91], v[14:15], v[86:87]
	v_pk_add_f32 v[92:93], v[16:17], v[88:89]
	v_lshl_add_u64 v[102:103], v[94:95], 2, v[102:103]
	s_cmp_eq_u64 s[80:81], 0
	global_store_dwordx4 v[102:103], v[90:93], off
	s_cbranch_scc1 .LBB0_821
	v_pk_mul_f32 v[102:103], v[82:83], v[90:91]
	v_pk_mul_f32 v[104:105], v[84:85], v[92:93]
	v_cvt_pk_bf16_f32 v102, v102, v103
	v_cvt_pk_bf16_f32 v103, v104, v105
	v_lshlrev_b64 v[104:105], 12, v[96:97]
	v_pk_mul_f32 v[90:91], v[90:91], v[90:91]
	v_pk_mul_f32 v[92:93], v[92:93], v[92:93]
	v_lshl_add_u64 v[104:105], s[20:21], 0, v[104:105]
	v_add_f32_e32 v0, v92, v93
	v_add_f32_e32 v90, v90, v91
	v_lshl_add_u64 v[104:105], v[94:95], 1, v[104:105]
	v_add_f32_e32 v0, v90, v0
	global_store_dwordx2 v[104:105], v[102:103], off
	s_nop 1
	v_mov_b32_dpp v90, v0 quad_perm:[1,0,3,2] row_mask:0xf bank_mask:0xf
	s_waitcnt lgkmcnt(0)
	v_add_f32_e32 v0, v0, v90
	s_nop 1
	v_mov_b32_dpp v90, v0 quad_perm:[2,3,0,1] row_mask:0xf bank_mask:0xf
	s_waitcnt lgkmcnt(0)
	v_add_f32_e32 v0, v0, v90
	s_nop 1
	v_mov_b32_dpp v90, v0 row_half_mirror row_mask:0xf bank_mask:0xf
	s_waitcnt lgkmcnt(0)
	v_add_f32_e32 v90, v0, v90
	s_nop 1
	v_mov_b32_dpp v91, v90 row_ror:8 row_mask:0xf bank_mask:0xf
	s_and_saveexec_b64 s[2:3], s[4:5]
	s_cbranch_execz .LBB0_820
	v_lshlrev_b64 v[92:93], 7, v[96:97]
	v_lshl_add_u64 v[92:93], s[42:43], 0, v[92:93]
	v_lshl_add_u64 v[92:93], s[0:1], 2, v[92:93]
	v_lshlrev_b32_e32 v0, 2, v139
	v_lshl_add_u64 v[92:93], v[92:93], 0, v[0:1]
	s_waitcnt lgkmcnt(0)
	v_add_f32_e32 v0, v90, v91
	global_store_dword v[92:93], v0, off

; DI unsigned pk2(float a, float b) { f32x2 v; v[0] = a; v[1] = b; return __builtin_bit_cast(unsigned, __builtin_convertvector(v, bf16v2)); }
; DI float shx_(float v, int m) { return __int_as_float(__builtin_amdgcn_ds_bpermute((lane_pinned_() ^ m) << 2, __float_as_int(v))); }
; DI int shx_(int v, int m) { return __builtin_amdgcn_ds_bpermute((lane_pinned_() ^ m) << 2, v); }
; DI void gemm_tile(const GD& g, int pm, int pn, bf16_t* shm) {
;     ...
;         for (int q = 0; q < 4; ++q) {
;           const int row_l = (pb8 * 4 + q) * 4 + (lane >> 4);
;           float4 v = *reinterpret_cast<const float4*>(stgw + row_l * 68 + c4);
;           const int grow = brow + ai * HALF + wr * 64 + row_l;
;           if (g.epi == 0) {
;             if (g.rowscale) {
;               const float rr = rsc[ai * HALF + wr * 64 + row_l];
;               v.x *= rr; v.y *= rr; v.z *= rr; v.w *= rr;
;             }
;             u32x2 o2; o2[0] = pk2(v.x, v.y); o2[1] = pk2(v.z, v.w);
;             *reinterpret_cast<u32x2*>((bf16_t*)g.C + (long)grow * ldc + gcol) = o2;
;           } else if (g.epi == 2) {
;             const float rr = rsc[ai * HALF + wr * 64 + row_l];
;             v.x *= rr; v.y *= rr; v.z *= rr; v.w *= rr;
;             *reinterpret_cast<float4*>((float*)g.C + (long)grow * ldc + gcol) = v;
;           } else {
;             float4 x = xs[q];
;             x.x += v.x; x.y += v.y; x.z += v.z; x.w += v.w;
;             *reinterpret_cast<float4*>((float*)g.C + (long)grow * ldc + gcol) = x;
;             if (g.gnext) {
;               u32x2 o2; o2[0] = pk2(x.x * gn.x, x.y * gn.y); o2[1] = pk2(x.z * gn.z, x.w * gn.w);
;               *reinterpret_cast<u32x2*>(g.hbout + (long)grow * DM + gcol) = o2;
;               float sq = (x.x * x.x + x.y * x.y) + (x.z * x.z + x.w * x.w);
;               sq += shx_(sq, 1); sq += shx_(sq, 2); sq += shx_(sq, 4); sq += shx_(sq, 8);
;               if ((lane & 15) == 0) g.ss[(long)grow * 32 + pn * 4 + wc] = sq;
;             }
.LBB0_839:
	v_mad_u64_u32 v[102:103], s[2:3], v96, s78, 0
	v_lshl_add_u64 v[102:103], v[102:103], 2, s[34:35]
	s_waitcnt lgkmcnt(0)
	v_pk_add_f32 v[90:91], v[6:7], v[86:87]
	v_pk_add_f32 v[92:93], v[8:9], v[88:89]
	v_lshl_add_u64 v[102:103], v[94:95], 2, v[102:103]
	s_cmp_eq_u64 s[80:81], 0
	global_store_dwordx4 v[102:103], v[90:93], off
	s_cbranch_scc1 .LBB0_843
	v_pk_mul_f32 v[102:103], v[82:83], v[90:91]
	v_pk_mul_f32 v[104:105], v[84:85], v[92:93]
	v_cvt_pk_bf16_f32 v102, v102, v103
	v_cvt_pk_bf16_f32 v103, v104, v105
	v_lshlrev_b64 v[104:105], 12, v[96:97]
	v_pk_mul_f32 v[90:91], v[90:91], v[90:91]
	v_pk_mul_f32 v[92:93], v[92:93], v[92:93]
	v_lshl_add_u64 v[104:105], s[20:21], 0, v[104:105]
	v_add_f32_e32 v0, v92, v93
	v_add_f32_e32 v90, v90, v91
	v_lshl_add_u64 v[104:105], v[94:95], 1, v[104:105]
	v_add_f32_e32 v0, v90, v0
	global_store_dwordx2 v[104:105], v[102:103], off
	s_nop 1
	v_mov_b32_dpp v90, v0 quad_perm:[1,0,3,2] row_mask:0xf bank_mask:0xf
	s_waitcnt lgkmcnt(0)
	v_add_f32_e32 v0, v0, v90
	s_nop 1
	v_mov_b32_dpp v90, v0 quad_perm:[2,3,0,1] row_mask:0xf bank_mask:0xf
	s_waitcnt lgkmcnt(0)
	v_add_f32_e32 v0, v0, v90
	s_nop 1
	v_mov_b32_dpp v90, v0 row_half_mirror row_mask:0xf bank_mask:0xf
	s_waitcnt lgkmcnt(0)
	v_add_f32_e32 v90, v0, v90
	s_nop 1
	v_mov_b32_dpp v91, v90 row_ror:8 row_mask:0xf bank_mask:0xf
	s_and_saveexec_b64 s[2:3], s[4:5]
	s_cbranch_execz .LBB0_842
	v_lshlrev_b64 v[92:93], 7, v[96:97]
	v_lshl_add_u64 v[92:93], s[42:43], 0, v[92:93]
	v_lshl_add_u64 v[92:93], s[0:1], 2, v[92:93]
	v_lshlrev_b32_e32 v0, 2, v139
	v_lshl_add_u64 v[92:93], v[92:93], 0, v[0:1]
	s_waitcnt lgkmcnt(0)
	v_add_f32_e32 v0, v90, v91
	global_store_dword v[92:93], v0, off

; DI unsigned pk2(float a, float b) { f32x2 v; v[0] = a; v[1] = b; return __builtin_bit_cast(unsigned, __builtin_convertvector(v, bf16v2)); }
; DI float shx_(float v, int m) { return __int_as_float(__builtin_amdgcn_ds_bpermute((lane_pinned_() ^ m) << 2, __float_as_int(v))); }
; DI int shx_(int v, int m) { return __builtin_amdgcn_ds_bpermute((lane_pinned_() ^ m) << 2, v); }
; DI void gemm_tile(const GD& g, int pm, int pn, bf16_t* shm) {
;     ...
;         for (int q = 0; q < 4; ++q) {
;           const int row_l = (pb8 * 4 + q) * 4 + (lane >> 4);
;           float4 v = *reinterpret_cast<const float4*>(stgw + row_l * 68 + c4);
;           const int grow = brow + ai * HALF + wr * 64 + row_l;
;           if (g.epi == 0) {
;             if (g.rowscale) {
;               const float rr = rsc[ai * HALF + wr * 64 + row_l];
;               v.x *= rr; v.y *= rr; v.z *= rr; v.w *= rr;
;             }
;             u32x2 o2; o2[0] = pk2(v.x, v.y); o2[1] = pk2(v.z, v.w);
;             *reinterpret_cast<u32x2*>((bf16_t*)g.C + (long)grow * ldc + gcol) = o2;
;           } else if (g.epi == 2) {
;             const float rr = rsc[ai * HALF + wr * 64 + row_l];
;             v.x *= rr; v.y *= rr; v.z *= rr; v.w *= rr;
;             *reinterpret_cast<float4*>((float*)g.C + (long)grow * ldc + gcol) = v;
;           } else {
;             float4 x = xs[q];
;             x.x += v.x; x.y += v.y; x.z += v.z; x.w += v.w;
;             *reinterpret_cast<float4*>((float*)g.C + (long)grow * ldc + gcol) = x;
;             if (g.gnext) {
;               u32x2 o2; o2[0] = pk2(x.x * gn.x, x.y * gn.y); o2[1] = pk2(x.z * gn.z, x.w * gn.w);
;               *reinterpret_cast<u32x2*>(g.hbout + (long)grow * DM + gcol) = o2;
;               float sq = (x.x * x.x + x.y * x.y) + (x.z * x.z + x.w * x.w);
;               sq += shx_(sq, 1); sq += shx_(sq, 2); sq += shx_(sq, 4); sq += shx_(sq, 8);
;               if ((lane & 15) == 0) g.ss[(long)grow * 32 + pn * 4 + wc] = sq;
;             }
.LBB0_855:
	v_mad_u64_u32 v[102:103], s[2:3], v96, s78, 0
	v_lshl_add_u64 v[102:103], v[102:103], 2, s[34:35]
	s_waitcnt lgkmcnt(0)
	v_pk_add_f32 v[90:91], v[10:11], v[86:87]
	v_pk_add_f32 v[92:93], v[12:13], v[88:89]
	v_lshl_add_u64 v[102:103], v[94:95], 2, v[102:103]
	s_cmp_eq_u64 s[80:81], 0
	global_store_dwordx4 v[102:103], v[90:93], off
	s_cbranch_scc1 .LBB0_859
	v_pk_mul_f32 v[102:103], v[82:83], v[90:91]
	v_pk_mul_f32 v[104:105], v[84:85], v[92:93]
	v_cvt_pk_bf16_f32 v102, v102, v103
	v_cvt_pk_bf16_f32 v103, v104, v105
	v_lshlrev_b64 v[104:105], 12, v[96:97]
	v_pk_mul_f32 v[90:91], v[90:91], v[90:91]
	v_pk_mul_f32 v[92:93], v[92:93], v[92:93]
	v_lshl_add_u64 v[104:105], s[20:21], 0, v[104:105]
	v_add_f32_e32 v0, v92, v93
	v_add_f32_e32 v90, v90, v91
	v_lshl_add_u64 v[104:105], v[94:95], 1, v[104:105]
	v_add_f32_e32 v0, v90, v0
	global_store_dwordx2 v[104:105], v[102:103], off
	s_nop 1
	v_mov_b32_dpp v90, v0 quad_perm:[1,0,3,2] row_mask:0xf bank_mask:0xf
	s_waitcnt lgkmcnt(0)
	v_add_f32_e32 v0, v0, v90
	s_nop 1
	v_mov_b32_dpp v90, v0 quad_perm:[2,3,0,1] row_mask:0xf bank_mask:0xf
	s_waitcnt lgkmcnt(0)
	v_add_f32_e32 v0, v0, v90
	s_nop 1
	v_mov_b32_dpp v90, v0 row_half_mirror row_mask:0xf bank_mask:0xf
	s_waitcnt lgkmcnt(0)
	v_add_f32_e32 v90, v0, v90
	s_nop 1
	v_mov_b32_dpp v91, v90 row_ror:8 row_mask:0xf bank_mask:0xf
	s_and_saveexec_b64 s[2:3], s[4:5]
	s_cbranch_execz .LBB0_858
	v_lshlrev_b64 v[92:93], 7, v[96:97]
	v_lshl_add_u64 v[92:93], s[42:43], 0, v[92:93]
	v_lshl_add_u64 v[92:93], s[0:1], 2, v[92:93]
	v_lshlrev_b32_e32 v0, 2, v139
	v_lshl_add_u64 v[92:93], v[92:93], 0, v[0:1]
	s_waitcnt lgkmcnt(0)
	v_add_f32_e32 v0, v90, v91
	global_store_dword v[92:93], v0, off

; DI unsigned pk2(float a, float b) { f32x2 v; v[0] = a; v[1] = b; return __builtin_bit_cast(unsigned, __builtin_convertvector(v, bf16v2)); }
; DI float shx_(float v, int m) { return __int_as_float(__builtin_amdgcn_ds_bpermute((lane_pinned_() ^ m) << 2, __float_as_int(v))); }
; DI int shx_(int v, int m) { return __builtin_amdgcn_ds_bpermute((lane_pinned_() ^ m) << 2, v); }
; DI void gemm_tile(const GD& g, int pm, int pn, bf16_t* shm) {
;     ...
;         for (int q = 0; q < 4; ++q) {
;           const int row_l = (pb8 * 4 + q) * 4 + (lane >> 4);
;           float4 v = *reinterpret_cast<const float4*>(stgw + row_l * 68 + c4);
;           const int grow = brow + ai * HALF + wr * 64 + row_l;
;           if (g.epi == 0) {
;             if (g.rowscale) {
;               const float rr = rsc[ai * HALF + wr * 64 + row_l];
;               v.x *= rr; v.y *= rr; v.z *= rr; v.w *= rr;
;             }
;             u32x2 o2; o2[0] = pk2(v.x, v.y); o2[1] = pk2(v.z, v.w);
;             *reinterpret_cast<u32x2*>((bf16_t*)g.C + (long)grow * ldc + gcol) = o2;
;           } else if (g.epi == 2) {
;             const float rr = rsc[ai * HALF + wr * 64 + row_l];
;             v.x *= rr; v.y *= rr; v.z *= rr; v.w *= rr;
;             *reinterpret_cast<float4*>((float*)g.C + (long)grow * ldc + gcol) = v;
;           } else {
;             float4 x = xs[q];
;             x.x += v.x; x.y += v.y; x.z += v.z; x.w += v.w;
;             *reinterpret_cast<float4*>((float*)g.C + (long)grow * ldc + gcol) = x;
;             if (g.gnext) {
;               u32x2 o2; o2[0] = pk2(x.x * gn.x, x.y * gn.y); o2[1] = pk2(x.z * gn.z, x.w * gn.w);
;               *reinterpret_cast<u32x2*>(g.hbout + (long)grow * DM + gcol) = o2;
;               float sq = (x.x * x.x + x.y * x.y) + (x.z * x.z + x.w * x.w);
;               sq += shx_(sq, 1); sq += shx_(sq, 2); sq += shx_(sq, 4); sq += shx_(sq, 8);
;               if ((lane & 15) == 0) g.ss[(long)grow * 32 + pn * 4 + wc] = sq;
;             }
.LBB0_871:
	v_mad_u64_u32 v[102:103], s[2:3], v96, s78, 0
	v_lshl_add_u64 v[102:103], v[102:103], 2, s[34:35]
	s_waitcnt lgkmcnt(0)
	v_pk_add_f32 v[90:91], v[2:3], v[86:87]
	v_pk_add_f32 v[92:93], v[4:5], v[88:89]
	v_lshl_add_u64 v[102:103], v[94:95], 2, v[102:103]
	s_cmp_eq_u64 s[80:81], 0
	global_store_dwordx4 v[102:103], v[90:93], off
	s_cbranch_scc1 .LBB0_875
	v_pk_mul_f32 v[82:83], v[82:83], v[90:91]
	v_pk_mul_f32 v[84:85], v[84:85], v[92:93]
	v_cvt_pk_bf16_f32 v82, v82, v83
	v_cvt_pk_bf16_f32 v83, v84, v85
	v_lshlrev_b64 v[84:85], 12, v[96:97]
	v_lshl_add_u64 v[84:85], s[20:21], 0, v[84:85]
	v_lshl_add_u64 v[84:85], v[94:95], 1, v[84:85]
	global_store_dwordx2 v[84:85], v[82:83], off
	v_pk_mul_f32 v[82:83], v[90:91], v[90:91]
	v_pk_mul_f32 v[84:85], v[92:93], v[92:93]
	v_add_f32_e32 v82, v82, v83
	v_add_f32_e32 v0, v84, v85
	v_add_f32_e32 v0, v82, v0
	s_nop 1
	v_mov_b32_dpp v82, v0 quad_perm:[1,0,3,2] row_mask:0xf bank_mask:0xf
	s_waitcnt lgkmcnt(0)
	v_add_f32_e32 v0, v0, v82
	s_nop 1
	v_mov_b32_dpp v82, v0 quad_perm:[2,3,0,1] row_mask:0xf bank_mask:0xf
	s_waitcnt lgkmcnt(0)
	v_add_f32_e32 v0, v0, v82
	s_nop 1
	v_mov_b32_dpp v82, v0 row_half_mirror row_mask:0xf bank_mask:0xf
	s_waitcnt lgkmcnt(0)
	v_add_f32_e32 v82, v0, v82
	s_nop 1
	v_mov_b32_dpp v83, v82 row_ror:8 row_mask:0xf bank_mask:0xf
	s_and_saveexec_b64 s[2:3], s[4:5]
	s_cbranch_execz .LBB0_874
	v_lshlrev_b64 v[84:85], 7, v[96:97]
	v_lshl_add_u64 v[84:85], s[42:43], 0, v[84:85]
	v_lshl_add_u64 v[84:85], s[0:1], 2, v[84:85]
	v_lshlrev_b32_e32 v0, 2, v139
	v_lshl_add_u64 v[84:85], v[84:85], 0, v[0:1]
	s_waitcnt lgkmcnt(0)
	v_add_f32_e32 v0, v82, v83
	global_store_dword v[84:85], v0, off
